# halfround: FFN-in 6th round split into 256 half-M units (MMA(1,x) skipped, 4-block epilogue); dead epilogue bodies removed
# baseline (speedup 1.0000x reference)
.LBB0_216:
	s_mov_b32 s98, 0
	v_mov_b32_e32 v18, v244
	s_cmp_lt_i32 s80, s34
	s_cselect_b64 s[4:5], -1, 0
	s_cmp_ge_i32 s80, s34
	v_readfirstlane_b32 s26, v18
	s_cbranch_scc1 .LBB0_222
	s_ashr_i32 s6, s80, 31
	s_lshr_b32 s6, s6, 29
	s_add_i32 s15, s80, s6
	s_and_b32 s6, s15, -8
	s_lshr_b32 s21, s34, 3
	s_sub_i32 s22, s80, s6
	s_cmp_gt_i32 s22, -1
	s_mov_b64 s[6:7], -1
	s_cbranch_scc0 .LBB0_219
	s_mul_i32 s18, s22, s21
	s_mov_b64 s[6:7], 0

.LBB0_227:
	s_mov_b32 s98, s100
	s_andn2_b64 vcc, exec, s[4:5]
	s_mov_b32 s60, s26
	s_mov_b32 s22, s46
	s_mov_b32 s61, s47
	s_mov_b64 s[42:43], s[0:1]
	s_mov_b64 s[90:91], s[88:89]
	s_cbranch_vccz .LBB0_365
.LBB0_228:
	s_add_i32 s49, s49, 1
	s_mul_hi_u32 s0, s49, 0xcccccccd
	s_lshr_b32 s8, s0, 2
	s_and_b64 s[0:1], s[24:25], exec
	s_cselect_b32 s0, s49, s8
	s_mul_i32 s1, s0, s53
	s_mul_hi_u32 s4, s0, s33
	s_add_i32 s1, s4, s1
	s_mul_i32 s0, s0, s33
	s_add_u32 s4, s0, s80
	s_addc_u32 s5, s1, s82
	s_mov_b32 s100, 0
	s_cmpk_lg_u32 s34, 0x580
	s_cbranch_scc1 .Lhr_done
	s_cmpk_lg_u32 s33, 0x100
	s_cbranch_scc1 .Lhr_done
	s_cmpk_lt_u32 s4, 0x500
	s_cbranch_scc1 .Lhr_done
	s_mov_b32 s100, 1
	s_cmpk_lt_u32 s4, 0x580
	s_cbranch_scc1 .Lhr_done
	s_mov_b32 s100, 0
	s_cmpk_gt_u32 s4, 0x5ff
	s_cbranch_scc1 .Lhr_done
	s_movk_i32 s100, 0x81
	s_add_i32 s4, s4, 0xffffff80
.Lhr_done:
	v_mov_b64_e32 v[0:1], s[34:35]
	v_cmp_lt_i64_e64 s[6:7], s[4:5], v[0:1]
	v_cmp_ge_i64_e32 vcc, s[4:5], v[0:1]
	v_cndmask_b32_e64 v0, 0, 1, s[36:37]
	v_cmp_ne_u32_e64 s[0:1], 1, v0
	s_cbranch_vccnz .LBB0_232
	s_ashr_i32 s5, s4, 31
	s_lshr_b32 s5, s5, 29
	s_add_i32 s5, s4, s5
	s_ashr_i32 s26, s5, 3
	s_and_b32 s5, s5, -8
	s_sub_i32 s4, s4, s5
	s_lshr_b32 s5, s4, 31
	s_or_b32 s5, s83, s5
	s_mul_i32 s4, s5, s4
	s_add_i32 s26, s4, s26
	s_abs_i32 s5, s26
	s_mul_hi_u32 s46, s5, s52
	s_mul_i32 s47, s46, s12
	s_sub_i32 s5, s5, s47
	s_ashr_i32 s4, s26, 31
	s_add_i32 s47, s46, 1
	s_sub_i32 s66, s5, s12
	s_cmp_ge_u32 s5, s12
	s_cselect_b32 s46, s47, s46
	s_cselect_b32 s5, s66, s5
	s_add_i32 s47, s46, 1
	s_cmp_ge_u32 s5, s12
	s_cselect_b32 s5, s47, s46
	s_xor_b32 s5, s5, s4
	s_sub_i32 s46, s5, s4
	s_lshl_b32 s4, s46, 3
	s_sub_i32 s5, s13, s4
	s_min_i32 s5, s5, 8
	s_abs_i32 s66, s5
	v_cvt_f32_u32_e32 v0, s66
	s_sub_i32 s89, 0, s66
	s_mul_i32 s46, s46, s12
	s_sub_i32 s47, s26, s46
	v_rcp_iflag_f32_e32 v0, v0
	s_abs_i32 s88, s47
	s_xor_b32 s26, s47, s5
	s_ashr_i32 s46, s26, 31
	v_mul_f32_e32 v0, 0x4f7ffffe, v0
	v_cvt_u32_f32_e32 v0, v0
	s_mov_b32 s26, 0
	v_readfirstlane_b32 s92, v0
	s_mul_i32 s89, s89, s92
	s_mul_hi_u32 s89, s92, s89
	s_add_i32 s92, s92, s89
	s_mul_hi_u32 s89, s88, s92
	s_mul_i32 s92, s89, s66
	s_sub_i32 s88, s88, s92
	s_add_i32 s92, s89, 1
	s_sub_i32 s93, s88, s66
	s_cmp_ge_u32 s88, s66
	s_cselect_b32 s89, s92, s89
	s_cselect_b32 s88, s93, s88
	s_add_i32 s92, s89, 1
	s_cmp_ge_u32 s88, s66
	s_cselect_b32 s66, s92, s89
	s_xor_b32 s66, s66, s46
	s_sub_i32 s66, s66, s46
	s_cmp_ge_i32 s66, s58
	s_cselect_b64 s[88:89], -1, 0
	s_and_b64 s[88:89], s[28:29], s[88:89]
	v_cndmask_b32_e64 v0, 0, 1, s[88:89]
	s_and_b64 vcc, exec, s[0:1]
	v_readfirstlane_b32 s46, v0
	s_add_i32 s46, s66, s46
	s_cbranch_vccnz .LBB0_231
	s_mul_i32 s8, s8, -5
	s_lshl_b32 s88, s46, 1
	s_add_i32 s26, s8, s49
	s_add_i32 s8, s26, s88
	s_add_i32 s8, s8, -3
	s_cmp_gt_i32 s26, 2
	s_cselect_b32 s46, s8, s46

.LBB0_242:
	s_mul_i32 s7, s18, s47
	s_mul_hi_i32 s6, s18, s47
	s_add_u32 s7, s76, s7
	s_addc_u32 s6, s77, s6
	s_add_u32 s88, s7, s0
	s_addc_u32 s89, s6, s1
	s_bitcmp1_b32 s100, 7
	s_cselect_b32 s6, s48, 0
	s_add_u32 s88, s88, s6
	s_addc_u32 s89, s89, 0

.LBB0_246:
	s_add_i32 s90, s42, 2
	s_add_u32 s91, s6, 0x80
	s_addc_u32 s43, s7, 0
	s_cmp_eq_u32 s72, s42
	s_cselect_b32 s43, s89, s43
	s_cselect_b32 s42, s88, s91
	s_cselect_b32 s93, s1, s66
	s_cselect_b32 s92, s0, s8
	ds_read_b128 v[128:131], v222
	ds_read_b128 v[132:135], v222 offset:1024
	ds_read_b128 v[136:139], v222 offset:2048
	ds_read_b128 v[140:143], v222 offset:3072
	ds_read_b128 v[168:171], v222 offset:16384
	ds_read_b128 v[172:175], v222 offset:17408
	ds_read_b128 v[176:179], v222 offset:18432
	ds_read_b128 v[180:183], v222 offset:19456
	s_add_i32 m0, s68, 0xc000
	ds_read_b128 v[190:193], v188
	ds_read_b128 v[194:197], v188 offset:1024
	ds_read_b128 v[198:201], v188 offset:2048
	ds_read_b128 v[202:205], v188 offset:3072
	ds_read_b128 v[206:209], v188 offset:4096
	ds_read_b128 v[210:213], v188 offset:5120
	ds_read_b128 v[214:217], v188 offset:6144
	ds_read_b128 v[218:221], v188 offset:7168
	global_load_lds_dwordx4 v162, s[6:7]
	s_add_i32 m0, s68, 0xe000
	s_nop 0
	global_load_lds_dwordx4 v164, s[6:7]
	s_waitcnt vmcnt(8)
	s_waitcnt lgkmcnt(0)
	s_barrier
	s_setprio 1
	s_waitcnt lgkmcnt(0)
	v_mfma_f32_16x16x32_bf16 v[124:127], v[128:131], v[190:193], v[124:127]
	v_mfma_f32_16x16x32_bf16 v[120:123], v[136:139], v[190:193], v[120:123]
	v_mfma_f32_16x16x32_bf16 v[116:119], v[128:131], v[198:201], v[116:119]
	v_mfma_f32_16x16x32_bf16 v[112:115], v[136:139], v[198:201], v[112:115]
	v_mfma_f32_16x16x32_bf16 v[100:103], v[128:131], v[206:209], v[100:103]
	v_mfma_f32_16x16x32_bf16 v[96:99], v[136:139], v[206:209], v[96:99]
	v_mfma_f32_16x16x32_bf16 v[84:87], v[128:131], v[214:217], v[84:87]
	v_mfma_f32_16x16x32_bf16 v[80:83], v[136:139], v[214:217], v[80:83]
	v_mfma_f32_16x16x32_bf16 v[124:127], v[132:135], v[194:197], v[124:127]
	v_mfma_f32_16x16x32_bf16 v[120:123], v[140:143], v[194:197], v[120:123]
	v_mfma_f32_16x16x32_bf16 v[116:119], v[132:135], v[202:205], v[116:119]
	v_mfma_f32_16x16x32_bf16 v[112:115], v[140:143], v[202:205], v[112:115]
	v_mfma_f32_16x16x32_bf16 v[100:103], v[132:135], v[210:213], v[100:103]
	v_mfma_f32_16x16x32_bf16 v[96:99], v[140:143], v[210:213], v[96:99]
	v_mfma_f32_16x16x32_bf16 v[84:87], v[132:135], v[218:221], v[84:87]
	v_mfma_f32_16x16x32_bf16 v[80:83], v[140:143], v[218:221], v[80:83]
	s_setprio 0
	s_setprio 1
	v_mfma_f32_16x16x32_bf16 v[108:111], v[168:171], v[190:193], v[108:111]
	v_mfma_f32_16x16x32_bf16 v[104:107], v[176:179], v[190:193], v[104:107]
	v_mfma_f32_16x16x32_bf16 v[92:95], v[168:171], v[198:201], v[92:95]
	v_mfma_f32_16x16x32_bf16 v[88:91], v[176:179], v[198:201], v[88:91]
	v_mfma_f32_16x16x32_bf16 v[76:79], v[168:171], v[206:209], v[76:79]
	v_mfma_f32_16x16x32_bf16 v[72:75], v[176:179], v[206:209], v[72:75]
	v_mfma_f32_16x16x32_bf16 v[68:71], v[168:171], v[214:217], v[68:71]
	v_mfma_f32_16x16x32_bf16 v[64:67], v[176:179], v[214:217], v[64:67]
	v_mfma_f32_16x16x32_bf16 v[108:111], v[172:175], v[194:197], v[108:111]
	v_mfma_f32_16x16x32_bf16 v[104:107], v[180:183], v[194:197], v[104:107]
	v_mfma_f32_16x16x32_bf16 v[92:95], v[172:175], v[202:205], v[92:95]
	v_mfma_f32_16x16x32_bf16 v[88:91], v[180:183], v[202:205], v[88:91]
	v_mfma_f32_16x16x32_bf16 v[76:79], v[172:175], v[210:213], v[76:79]
	v_mfma_f32_16x16x32_bf16 v[72:75], v[180:183], v[210:213], v[72:75]
	v_mfma_f32_16x16x32_bf16 v[68:71], v[172:175], v[218:221], v[68:71]
	v_mfma_f32_16x16x32_bf16 v[64:67], v[180:183], v[218:221], v[64:67]
	s_setprio 0
	s_barrier
	s_add_i32 m0, s15, 0x10000
	ds_read_b128 v[190:193], v188 offset:16384
	ds_read_b128 v[194:197], v188 offset:17408
	ds_read_b128 v[198:201], v188 offset:18432
	ds_read_b128 v[202:205], v188 offset:19456
	ds_read_b128 v[206:209], v188 offset:20480
	ds_read_b128 v[210:213], v188 offset:21504
	ds_read_b128 v[214:217], v188 offset:22528
	ds_read_b128 v[218:221], v188 offset:23552
	global_load_lds_dwordx4 v148, s[92:93]
	s_add_i32 m0, s15, 0x12000
	s_nop 0
	global_load_lds_dwordx4 v152, s[92:93]
	s_add_i32 m0, s15, 0x14000
	s_add_u32 s92, s92, s21
	s_addc_u32 s93, s93, 0
	global_load_lds_dwordx4 v148, s[92:93]
	s_add_i32 m0, s15, 0x16000
	s_nop 0
	global_load_lds_dwordx4 v152, s[92:93]
	s_mov_b32 m0, s68
	s_nop 0
	global_load_lds_dwordx4 v146, s[42:43]
	s_mov_b32 m0, s23
	s_nop 0
	global_load_lds_dwordx4 v150, s[42:43]
	s_waitcnt vmcnt(8)
	s_waitcnt lgkmcnt(0)
	s_barrier
	s_cmp_lg_u32 s98, 0
	s_cbranch_scc1 .Lhr_k2
	s_setprio 1
	s_waitcnt lgkmcnt(0)
	v_mfma_f32_16x16x32_bf16 v[60:63], v[128:131], v[190:193], v[60:63]
	v_mfma_f32_16x16x32_bf16 v[56:59], v[136:139], v[190:193], v[56:59]
	v_mfma_f32_16x16x32_bf16 v[52:55], v[128:131], v[198:201], v[52:55]
	v_mfma_f32_16x16x32_bf16 v[48:51], v[136:139], v[198:201], v[48:51]
	v_mfma_f32_16x16x32_bf16 v[36:39], v[128:131], v[206:209], v[36:39]
	v_mfma_f32_16x16x32_bf16 v[32:35], v[136:139], v[206:209], v[32:35]
	v_mfma_f32_16x16x32_bf16 v[20:23], v[128:131], v[214:217], v[20:23]
	v_mfma_f32_16x16x32_bf16 v[16:19], v[136:139], v[214:217], v[16:19]
	v_mfma_f32_16x16x32_bf16 v[60:63], v[132:135], v[194:197], v[60:63]
	v_mfma_f32_16x16x32_bf16 v[56:59], v[140:143], v[194:197], v[56:59]
	v_mfma_f32_16x16x32_bf16 v[52:55], v[132:135], v[202:205], v[52:55]
	v_mfma_f32_16x16x32_bf16 v[48:51], v[140:143], v[202:205], v[48:51]
	v_mfma_f32_16x16x32_bf16 v[36:39], v[132:135], v[210:213], v[36:39]
	v_mfma_f32_16x16x32_bf16 v[32:35], v[140:143], v[210:213], v[32:35]
	v_mfma_f32_16x16x32_bf16 v[20:23], v[132:135], v[218:221], v[20:23]
	v_mfma_f32_16x16x32_bf16 v[16:19], v[140:143], v[218:221], v[16:19]
	s_setprio 0
	s_setprio 1
	v_mfma_f32_16x16x32_bf16 v[44:47], v[168:171], v[190:193], v[44:47]
	v_mfma_f32_16x16x32_bf16 v[40:43], v[176:179], v[190:193], v[40:43]
	v_mfma_f32_16x16x32_bf16 v[28:31], v[168:171], v[198:201], v[28:31]
	v_mfma_f32_16x16x32_bf16 v[24:27], v[176:179], v[198:201], v[24:27]
	v_mfma_f32_16x16x32_bf16 v[12:15], v[168:171], v[206:209], v[12:15]
	v_mfma_f32_16x16x32_bf16 v[8:11], v[176:179], v[206:209], v[8:11]
	v_mfma_f32_16x16x32_bf16 v[4:7], v[168:171], v[214:217], v[4:7]
	v_mfma_f32_16x16x32_bf16 v[0:3], v[176:179], v[214:217], v[0:3]
	v_mfma_f32_16x16x32_bf16 v[44:47], v[172:175], v[194:197], v[44:47]
	v_mfma_f32_16x16x32_bf16 v[40:43], v[180:183], v[194:197], v[40:43]
	v_mfma_f32_16x16x32_bf16 v[28:31], v[172:175], v[202:205], v[28:31]
	v_mfma_f32_16x16x32_bf16 v[24:27], v[180:183], v[202:205], v[24:27]
	v_mfma_f32_16x16x32_bf16 v[12:15], v[172:175], v[210:213], v[12:15]
	v_mfma_f32_16x16x32_bf16 v[8:11], v[180:183], v[210:213], v[8:11]
	v_mfma_f32_16x16x32_bf16 v[4:7], v[172:175], v[218:221], v[4:7]
	v_mfma_f32_16x16x32_bf16 v[0:3], v[180:183], v[218:221], v[0:3]
	s_setprio 0
.Lhr_k2:
	s_barrier
	ds_read_b128 v[128:131], v222 offset:32768
	ds_read_b128 v[132:135], v222 offset:33792
	ds_read_b128 v[136:139], v222 offset:34816
	ds_read_b128 v[140:143], v222 offset:35840
	ds_read_b128 v[168:171], v222 offset:49152
	ds_read_b128 v[172:175], v222 offset:50176
	ds_read_b128 v[176:179], v222 offset:51200
	ds_read_b128 v[180:183], v222 offset:52224
	s_add_u32 s42, s42, s48
	s_addc_u32 s43, s43, 0
	s_mov_b32 m0, s40
	ds_read_b128 v[190:193], v188 offset:32768
	ds_read_b128 v[194:197], v188 offset:33792
	ds_read_b128 v[198:201], v188 offset:34816
	ds_read_b128 v[202:205], v188 offset:35840
	ds_read_b128 v[206:209], v188 offset:36864
	ds_read_b128 v[210:213], v188 offset:37888
	ds_read_b128 v[214:217], v188 offset:38912
	ds_read_b128 v[218:221], v188 offset:39936
	global_load_lds_dwordx4 v146, s[42:43]
	s_mov_b32 m0, s41
	s_nop 0
	global_load_lds_dwordx4 v150, s[42:43]
	s_waitcnt vmcnt(8)
	s_waitcnt lgkmcnt(0)
	s_barrier
	s_setprio 1
	s_waitcnt lgkmcnt(0)
	v_mfma_f32_16x16x32_bf16 v[124:127], v[128:131], v[190:193], v[124:127]
	v_mfma_f32_16x16x32_bf16 v[120:123], v[136:139], v[190:193], v[120:123]
	v_mfma_f32_16x16x32_bf16 v[116:119], v[128:131], v[198:201], v[116:119]
	v_mfma_f32_16x16x32_bf16 v[112:115], v[136:139], v[198:201], v[112:115]
	v_mfma_f32_16x16x32_bf16 v[100:103], v[128:131], v[206:209], v[100:103]
	v_mfma_f32_16x16x32_bf16 v[96:99], v[136:139], v[206:209], v[96:99]
	v_mfma_f32_16x16x32_bf16 v[84:87], v[128:131], v[214:217], v[84:87]
	v_mfma_f32_16x16x32_bf16 v[80:83], v[136:139], v[214:217], v[80:83]
	v_mfma_f32_16x16x32_bf16 v[124:127], v[132:135], v[194:197], v[124:127]
	v_mfma_f32_16x16x32_bf16 v[120:123], v[140:143], v[194:197], v[120:123]
	v_mfma_f32_16x16x32_bf16 v[116:119], v[132:135], v[202:205], v[116:119]
	v_mfma_f32_16x16x32_bf16 v[112:115], v[140:143], v[202:205], v[112:115]
	v_mfma_f32_16x16x32_bf16 v[100:103], v[132:135], v[210:213], v[100:103]
	v_mfma_f32_16x16x32_bf16 v[96:99], v[140:143], v[210:213], v[96:99]
	v_mfma_f32_16x16x32_bf16 v[84:87], v[132:135], v[218:221], v[84:87]
	v_mfma_f32_16x16x32_bf16 v[80:83], v[140:143], v[218:221], v[80:83]
	s_setprio 0
	s_setprio 1
	v_mfma_f32_16x16x32_bf16 v[108:111], v[168:171], v[190:193], v[108:111]
	v_mfma_f32_16x16x32_bf16 v[104:107], v[176:179], v[190:193], v[104:107]
	v_mfma_f32_16x16x32_bf16 v[92:95], v[168:171], v[198:201], v[92:95]
	v_mfma_f32_16x16x32_bf16 v[88:91], v[176:179], v[198:201], v[88:91]
	v_mfma_f32_16x16x32_bf16 v[76:79], v[168:171], v[206:209], v[76:79]
	v_mfma_f32_16x16x32_bf16 v[72:75], v[176:179], v[206:209], v[72:75]
	v_mfma_f32_16x16x32_bf16 v[68:71], v[168:171], v[214:217], v[68:71]
	v_mfma_f32_16x16x32_bf16 v[64:67], v[176:179], v[214:217], v[64:67]
	v_mfma_f32_16x16x32_bf16 v[108:111], v[172:175], v[194:197], v[108:111]
	v_mfma_f32_16x16x32_bf16 v[104:107], v[180:183], v[194:197], v[104:107]
	v_mfma_f32_16x16x32_bf16 v[92:95], v[172:175], v[202:205], v[92:95]
	v_mfma_f32_16x16x32_bf16 v[88:91], v[180:183], v[202:205], v[88:91]
	v_mfma_f32_16x16x32_bf16 v[76:79], v[172:175], v[210:213], v[76:79]
	v_mfma_f32_16x16x32_bf16 v[72:75], v[180:183], v[210:213], v[72:75]
	v_mfma_f32_16x16x32_bf16 v[68:71], v[172:175], v[218:221], v[68:71]
	v_mfma_f32_16x16x32_bf16 v[64:67], v[180:183], v[218:221], v[64:67]
	s_setprio 0
	s_barrier
	s_sub_u32 s92, s92, s21
	s_subb_u32 s93, s93, 0
	s_add_i32 m0, s15, 0x17f80
	ds_read_b128 v[190:193], v188 offset:49152
	ds_read_b128 v[194:197], v188 offset:50176
	ds_read_b128 v[198:201], v188 offset:51200
	ds_read_b128 v[202:205], v188 offset:52224
	ds_read_b128 v[206:209], v188 offset:53248
	ds_read_b128 v[210:213], v188 offset:54272
	ds_read_b128 v[214:217], v188 offset:55296
	ds_read_b128 v[218:221], v188 offset:56320
	global_load_lds_dwordx4 v148, s[92:93] offset:128
	s_add_i32 m0, s15, 0x19f80
	s_nop 0
	global_load_lds_dwordx4 v152, s[92:93] offset:128
	s_add_u32 s92, s92, s21
	s_addc_u32 s93, s93, 0
	s_add_i32 m0, s15, 0x1bf80
	s_add_u32 s6, s6, 0x100
	s_addc_u32 s7, s7, 0
	global_load_lds_dwordx4 v148, s[92:93] offset:128
	s_add_i32 m0, s15, 0x1df80
	s_sub_u32 s42, s42, s48
	s_subb_u32 s43, s43, 0
	global_load_lds_dwordx4 v152, s[92:93] offset:128
	s_add_i32 m0, s64, 0xffffff80
	s_add_u32 s8, s8, 0x100
	s_addc_u32 s66, s66, 0
	global_load_lds_dwordx4 v146, s[42:43] offset:128
	s_add_i32 m0, s65, 0xffffff80
	s_nop 0
	global_load_lds_dwordx4 v150, s[42:43] offset:128
	s_waitcnt vmcnt(8)
	s_waitcnt lgkmcnt(0)
	s_barrier
	s_cmp_lg_u32 s98, 0
	s_cbranch_scc1 .Lhr_k4
	s_setprio 1
	s_waitcnt lgkmcnt(0)
	v_mfma_f32_16x16x32_bf16 v[60:63], v[128:131], v[190:193], v[60:63]
	v_mfma_f32_16x16x32_bf16 v[56:59], v[136:139], v[190:193], v[56:59]
	v_mfma_f32_16x16x32_bf16 v[52:55], v[128:131], v[198:201], v[52:55]
	v_mfma_f32_16x16x32_bf16 v[48:51], v[136:139], v[198:201], v[48:51]
	v_mfma_f32_16x16x32_bf16 v[36:39], v[128:131], v[206:209], v[36:39]
	v_mfma_f32_16x16x32_bf16 v[32:35], v[136:139], v[206:209], v[32:35]
	v_mfma_f32_16x16x32_bf16 v[20:23], v[128:131], v[214:217], v[20:23]
	v_mfma_f32_16x16x32_bf16 v[16:19], v[136:139], v[214:217], v[16:19]
	v_mfma_f32_16x16x32_bf16 v[60:63], v[132:135], v[194:197], v[60:63]
	v_mfma_f32_16x16x32_bf16 v[56:59], v[140:143], v[194:197], v[56:59]
	v_mfma_f32_16x16x32_bf16 v[52:55], v[132:135], v[202:205], v[52:55]
	v_mfma_f32_16x16x32_bf16 v[48:51], v[140:143], v[202:205], v[48:51]
	v_mfma_f32_16x16x32_bf16 v[36:39], v[132:135], v[210:213], v[36:39]
	v_mfma_f32_16x16x32_bf16 v[32:35], v[140:143], v[210:213], v[32:35]
	v_mfma_f32_16x16x32_bf16 v[20:23], v[132:135], v[218:221], v[20:23]
	v_mfma_f32_16x16x32_bf16 v[16:19], v[140:143], v[218:221], v[16:19]
	s_setprio 0
	s_setprio 1
	v_mfma_f32_16x16x32_bf16 v[44:47], v[168:171], v[190:193], v[44:47]
	v_mfma_f32_16x16x32_bf16 v[40:43], v[176:179], v[190:193], v[40:43]
	v_mfma_f32_16x16x32_bf16 v[28:31], v[168:171], v[198:201], v[28:31]
	v_mfma_f32_16x16x32_bf16 v[24:27], v[176:179], v[198:201], v[24:27]
	v_mfma_f32_16x16x32_bf16 v[12:15], v[168:171], v[206:209], v[12:15]
	v_mfma_f32_16x16x32_bf16 v[8:11], v[176:179], v[206:209], v[8:11]
	v_mfma_f32_16x16x32_bf16 v[4:7], v[168:171], v[214:217], v[4:7]
	v_mfma_f32_16x16x32_bf16 v[0:3], v[176:179], v[214:217], v[0:3]
	v_mfma_f32_16x16x32_bf16 v[44:47], v[172:175], v[194:197], v[44:47]
	v_mfma_f32_16x16x32_bf16 v[40:43], v[180:183], v[194:197], v[40:43]
	v_mfma_f32_16x16x32_bf16 v[28:31], v[172:175], v[202:205], v[28:31]
	v_mfma_f32_16x16x32_bf16 v[24:27], v[180:183], v[202:205], v[24:27]
	v_mfma_f32_16x16x32_bf16 v[12:15], v[172:175], v[210:213], v[12:15]
	v_mfma_f32_16x16x32_bf16 v[8:11], v[180:183], v[210:213], v[8:11]
	v_mfma_f32_16x16x32_bf16 v[4:7], v[172:175], v[218:221], v[4:7]
	v_mfma_f32_16x16x32_bf16 v[0:3], v[180:183], v[218:221], v[0:3]
	s_setprio 0
.Lhr_k4:
	s_barrier
	s_cmp_ge_u32 s90, s55
	s_mov_b32 s42, s90
	s_cbranch_scc0 .LBB0_246
	s_and_b64 vcc, exec, s[86:87]
	s_cbranch_vccz .LBB0_249
	s_barrier

.LBB0_271:
	s_lshl_b32 s66, s61, 8
	s_add_i32 s66, s66, s73
	s_add_i32 s66, s66, s98
	s_and_b32 s66, s66, -2
	s_cmp_lg_u32 s8, 8
	v_or_b32_e32 v168, s66, v155
	s_mov_b64 s[42:43], -1
	s_cbranch_scc0 .LBB0_277
	s_add_u32 s90, s62, s6
	s_addc_u32 s91, s63, s7
	s_cmp_gt_u32 s8, 1
	s_mov_b64 s[6:7], -1
	s_cbranch_scc0 .LBB0_359
	s_cmp_eq_u32 s8, 7
	s_cselect_b32 s6, s3, 0x10000000
	s_add_u32 s94, s62, s6
	s_addc_u32 s95, s63, 0
	s_mov_b64 s[96:97], -1
	s_mov_b64 s[6:7], 0
	s_cmp_lt_i32 s8, 4
	s_mov_b64 s[42:43], 0
	s_cbranch_scc1 .LBB0_285
	s_cmp_gt_i32 s8, 5
	s_cbranch_scc0 .LBB0_282
	s_cmp_gt_i32 s8, 8
	s_cbranch_scc0 .LBB0_279
	s_cmp_eq_u32 s8, 9
	s_mov_b64 s[42:43], -1
	s_cselect_b64 s[96:97], -1, 0
	s_cbranch_execz .LBB0_280
	s_branch .LBB0_282

.LBB0_280:
	s_cmp_eq_u32 s8, 6
	s_mov_b64 s[42:43], -1
	s_cbranch_scc0 .LBB0_282
.LBB0_282:
	s_and_b64 vcc, exec, s[96:97]
	s_cbranch_vccz .LBB0_284
.LBB0_284:
	s_mov_b64 s[96:97], 0

.LBB0_356:
	s_andn2_b64 vcc, exec, s[6:7]
	s_cbranch_vccnz .LBB0_358
	v_mul_f32_e32 v132, 0xbfb8aa3b, v124
	v_mul_f32_e32 v133, 0xbfb8aa3b, v125
	v_mul_f32_e32 v134, 0xbfb8aa3b, v126
	v_mul_f32_e32 v135, 0xbfb8aa3b, v127
	v_mul_f32_e32 v136, 0xbfb8aa3b, v120
	v_mul_f32_e32 v137, 0xbfb8aa3b, v121
	v_mul_f32_e32 v138, 0xbfb8aa3b, v122
	v_mul_f32_e32 v139, 0xbfb8aa3b, v123
	v_exp_f32_e32 v132, v132
	v_exp_f32_e32 v133, v133
	v_exp_f32_e32 v134, v134
	v_exp_f32_e32 v135, v135
	v_exp_f32_e32 v136, v136
	v_exp_f32_e32 v137, v137
	v_exp_f32_e32 v138, v138
	v_exp_f32_e32 v139, v139
	v_mov_b64_e32 v[128:129], s[90:91]
	s_movk_i32 s66, 0x1600
	v_add_f32_e32 v132, 1.0, v132
	v_add_f32_e32 v133, 1.0, v133
	v_add_f32_e32 v134, 1.0, v134
	v_add_f32_e32 v135, 1.0, v135
	v_add_f32_e32 v136, 1.0, v136
	v_add_f32_e32 v137, 1.0, v137
	v_add_f32_e32 v138, 1.0, v138
	v_add_f32_e32 v139, 1.0, v139
	v_mad_i64_i32 v[130:131], s[6:7], v168, s66, v[128:129]
	v_rcp_f32_e32 v132, v132
	v_rcp_f32_e32 v133, v133
	v_rcp_f32_e32 v134, v134
	v_rcp_f32_e32 v135, v135
	v_rcp_f32_e32 v136, v136
	v_rcp_f32_e32 v137, v137
	v_rcp_f32_e32 v138, v138
	v_rcp_f32_e32 v139, v139
	s_lshl_b32 s6, s22, 7
	s_ashr_i32 s7, s6, 31
	s_lshl_b64 s[6:7], s[6:7], 1
	v_lshl_add_u64 v[130:131], v[130:131], 0, s[6:7]
	s_lshl_b32 s42, s81, 1
	s_mov_b32 s43, s27
	v_pk_mul_f32 v[132:133], v[124:125], v[132:133]
	v_pk_mul_f32 v[134:135], v[126:127], v[134:135]
	v_pk_mul_f32 v[136:137], v[120:121], v[136:137]
	v_pk_mul_f32 v[138:139], v[122:123], v[138:139]
	v_lshl_add_u64 v[130:131], v[130:131], 0, s[42:43]
	v_pk_mul_f32 v[132:133], v[132:133], v[108:109]
	v_pk_mul_f32 v[134:135], v[134:135], v[110:111]
	v_pk_mul_f32 v[136:137], v[136:137], v[104:105]
	v_pk_mul_f32 v[138:139], v[138:139], v[106:107]
	v_lshlrev_b32_e32 v144, 1, v154
	v_lshl_add_u64 v[140:141], v[130:131], 0, v[144:145]
	v_cvt_pk_bf16_f32 v130, v132, v133
	v_cvt_pk_bf16_f32 v131, v134, v135
	v_cvt_pk_bf16_f32 v132, v136, v137
	v_cvt_pk_bf16_f32 v133, v138, v139
	global_store_dwordx4 v[140:141], v[130:133], off
	v_mul_f32_e32 v134, 0xbfb8aa3b, v118
	v_mul_f32_e32 v135, 0xbfb8aa3b, v119
	v_mul_f32_e32 v130, 0xbfb8aa3b, v116
	v_mul_f32_e32 v131, 0xbfb8aa3b, v117
	v_mul_f32_e32 v136, 0xbfb8aa3b, v112
	v_mul_f32_e32 v137, 0xbfb8aa3b, v113
	v_mul_f32_e32 v138, 0xbfb8aa3b, v114
	v_mul_f32_e32 v139, 0xbfb8aa3b, v115
	v_exp_f32_e32 v130, v130
	v_exp_f32_e32 v131, v131
	v_exp_f32_e32 v134, v134
	v_exp_f32_e32 v135, v135
	v_exp_f32_e32 v136, v136
	v_exp_f32_e32 v137, v137
	v_exp_f32_e32 v138, v138
	v_exp_f32_e32 v139, v139
	v_add_f32_e32 v130, 1.0, v130
	v_add_f32_e32 v131, 1.0, v131
	v_add_f32_e32 v134, 1.0, v134
	v_add_f32_e32 v135, 1.0, v135
	v_add_f32_e32 v136, 1.0, v136
	v_add_f32_e32 v137, 1.0, v137
	v_add_f32_e32 v138, 1.0, v138
	v_add_f32_e32 v139, 1.0, v139
	v_rcp_f32_e32 v130, v130
	v_rcp_f32_e32 v131, v131
	v_rcp_f32_e32 v134, v134
	v_rcp_f32_e32 v135, v135
	v_rcp_f32_e32 v136, v136
	v_rcp_f32_e32 v137, v137
	v_rcp_f32_e32 v138, v138
	v_rcp_f32_e32 v139, v139
	v_or_b32_e32 v132, 16, v168
	v_mad_i64_i32 v[132:133], s[60:61], v132, s66, v[128:129]
	v_lshl_add_u64 v[132:133], v[132:133], 0, s[6:7]
	v_pk_mul_f32 v[130:131], v[116:117], v[130:131]
	v_pk_mul_f32 v[134:135], v[118:119], v[134:135]
	v_pk_mul_f32 v[136:137], v[112:113], v[136:137]
	v_pk_mul_f32 v[138:139], v[114:115], v[138:139]
	v_lshl_add_u64 v[132:133], v[132:133], 0, s[42:43]
	v_pk_mul_f32 v[130:131], v[130:131], v[92:93]
	v_pk_mul_f32 v[134:135], v[134:135], v[94:95]
	v_pk_mul_f32 v[136:137], v[136:137], v[88:89]
	v_pk_mul_f32 v[138:139], v[138:139], v[90:91]
	v_lshl_add_u64 v[140:141], v[132:133], 0, v[144:145]
	v_cvt_pk_bf16_f32 v130, v130, v131
	v_cvt_pk_bf16_f32 v131, v134, v135
	v_cvt_pk_bf16_f32 v132, v136, v137
	v_cvt_pk_bf16_f32 v133, v138, v139
	global_store_dwordx4 v[140:141], v[130:133], off
	v_mul_f32_e32 v134, 0xbfb8aa3b, v102
	v_mul_f32_e32 v135, 0xbfb8aa3b, v103
	v_mul_f32_e32 v130, 0xbfb8aa3b, v100
	v_mul_f32_e32 v131, 0xbfb8aa3b, v101
	v_mul_f32_e32 v136, 0xbfb8aa3b, v96
	v_mul_f32_e32 v137, 0xbfb8aa3b, v97
	v_mul_f32_e32 v138, 0xbfb8aa3b, v98
	v_mul_f32_e32 v139, 0xbfb8aa3b, v99
	v_exp_f32_e32 v130, v130
	v_exp_f32_e32 v131, v131
	v_exp_f32_e32 v134, v134
	v_exp_f32_e32 v135, v135
	v_exp_f32_e32 v136, v136
	v_exp_f32_e32 v137, v137
	v_exp_f32_e32 v138, v138
	v_exp_f32_e32 v139, v139
	v_add_f32_e32 v130, 1.0, v130
	v_add_f32_e32 v131, 1.0, v131
	v_add_f32_e32 v134, 1.0, v134
	v_add_f32_e32 v135, 1.0, v135
	v_add_f32_e32 v136, 1.0, v136
	v_add_f32_e32 v137, 1.0, v137
	v_add_f32_e32 v138, 1.0, v138
	v_add_f32_e32 v139, 1.0, v139
	v_rcp_f32_e32 v130, v130
	v_rcp_f32_e32 v131, v131
	v_rcp_f32_e32 v134, v134
	v_rcp_f32_e32 v135, v135
	v_rcp_f32_e32 v136, v136
	v_rcp_f32_e32 v137, v137
	v_rcp_f32_e32 v138, v138
	v_rcp_f32_e32 v139, v139
	v_or_b32_e32 v132, 32, v168
	v_mad_i64_i32 v[132:133], s[60:61], v132, s66, v[128:129]
	v_lshl_add_u64 v[132:133], v[132:133], 0, s[6:7]
	v_pk_mul_f32 v[130:131], v[100:101], v[130:131]
	v_pk_mul_f32 v[134:135], v[102:103], v[134:135]
	v_pk_mul_f32 v[136:137], v[96:97], v[136:137]
	v_pk_mul_f32 v[138:139], v[98:99], v[138:139]
	v_lshl_add_u64 v[132:133], v[132:133], 0, s[42:43]
	v_pk_mul_f32 v[130:131], v[130:131], v[76:77]
	v_pk_mul_f32 v[134:135], v[134:135], v[78:79]
	v_pk_mul_f32 v[136:137], v[136:137], v[72:73]
	v_pk_mul_f32 v[138:139], v[138:139], v[74:75]
	v_lshl_add_u64 v[140:141], v[132:133], 0, v[144:145]
	v_cvt_pk_bf16_f32 v130, v130, v131
	v_cvt_pk_bf16_f32 v131, v134, v135
	v_cvt_pk_bf16_f32 v132, v136, v137
	v_cvt_pk_bf16_f32 v133, v138, v139
	global_store_dwordx4 v[140:141], v[130:133], off
	v_mul_f32_e32 v134, 0xbfb8aa3b, v86
	v_mul_f32_e32 v135, 0xbfb8aa3b, v87
	v_mul_f32_e32 v130, 0xbfb8aa3b, v84
	v_mul_f32_e32 v131, 0xbfb8aa3b, v85
	v_mul_f32_e32 v136, 0xbfb8aa3b, v80
	v_mul_f32_e32 v137, 0xbfb8aa3b, v81
	v_mul_f32_e32 v138, 0xbfb8aa3b, v82
	v_mul_f32_e32 v139, 0xbfb8aa3b, v83
	v_exp_f32_e32 v130, v130
	v_exp_f32_e32 v131, v131
	v_exp_f32_e32 v134, v134
	v_exp_f32_e32 v135, v135
	v_exp_f32_e32 v136, v136
	v_exp_f32_e32 v137, v137
	v_exp_f32_e32 v138, v138
	v_exp_f32_e32 v139, v139
	v_add_f32_e32 v130, 1.0, v130
	v_add_f32_e32 v131, 1.0, v131
	v_add_f32_e32 v134, 1.0, v134
	v_add_f32_e32 v135, 1.0, v135
	v_add_f32_e32 v136, 1.0, v136
	v_add_f32_e32 v137, 1.0, v137
	v_add_f32_e32 v138, 1.0, v138
	v_add_f32_e32 v139, 1.0, v139
	v_rcp_f32_e32 v130, v130
	v_rcp_f32_e32 v131, v131
	v_rcp_f32_e32 v134, v134
	v_rcp_f32_e32 v135, v135
	v_rcp_f32_e32 v136, v136
	v_rcp_f32_e32 v137, v137
	v_rcp_f32_e32 v138, v138
	v_rcp_f32_e32 v139, v139
	v_or_b32_e32 v132, 48, v168
	v_mad_i64_i32 v[132:133], s[60:61], v132, s66, v[128:129]
	v_lshl_add_u64 v[132:133], v[132:133], 0, s[6:7]
	v_pk_mul_f32 v[130:131], v[84:85], v[130:131]
	v_pk_mul_f32 v[134:135], v[86:87], v[134:135]
	v_pk_mul_f32 v[136:137], v[80:81], v[136:137]
	v_pk_mul_f32 v[138:139], v[82:83], v[138:139]
	v_lshl_add_u64 v[132:133], v[132:133], 0, s[42:43]
	v_pk_mul_f32 v[130:131], v[130:131], v[68:69]
	v_pk_mul_f32 v[134:135], v[134:135], v[70:71]
	v_pk_mul_f32 v[136:137], v[136:137], v[64:65]
	v_pk_mul_f32 v[138:139], v[138:139], v[66:67]
	v_lshl_add_u64 v[140:141], v[132:133], 0, v[144:145]
	v_cvt_pk_bf16_f32 v130, v130, v131
	v_cvt_pk_bf16_f32 v131, v134, v135
	v_cvt_pk_bf16_f32 v132, v136, v137
	v_cvt_pk_bf16_f32 v133, v138, v139
	global_store_dwordx4 v[140:141], v[130:133], off
	s_cmp_lg_u32 s98, 0
	s_cbranch_scc1 .LBB0_358
	v_mul_f32_e32 v134, 0xbfb8aa3b, v62
	v_mul_f32_e32 v135, 0xbfb8aa3b, v63
	v_mul_f32_e32 v130, 0xbfb8aa3b, v60
	v_mul_f32_e32 v131, 0xbfb8aa3b, v61
	v_mul_f32_e32 v136, 0xbfb8aa3b, v56
	v_mul_f32_e32 v137, 0xbfb8aa3b, v57
	v_mul_f32_e32 v138, 0xbfb8aa3b, v58
	v_mul_f32_e32 v139, 0xbfb8aa3b, v59
	v_exp_f32_e32 v130, v130
	v_exp_f32_e32 v131, v131
	v_exp_f32_e32 v134, v134
	v_exp_f32_e32 v135, v135
	v_exp_f32_e32 v136, v136
	v_exp_f32_e32 v137, v137
	v_exp_f32_e32 v138, v138
	v_exp_f32_e32 v139, v139
	v_add_f32_e32 v130, 1.0, v130
	v_add_f32_e32 v131, 1.0, v131
	v_add_f32_e32 v134, 1.0, v134
	v_add_f32_e32 v135, 1.0, v135
	v_add_f32_e32 v136, 1.0, v136
	v_add_f32_e32 v137, 1.0, v137
	v_add_f32_e32 v138, 1.0, v138
	v_add_f32_e32 v139, 1.0, v139
	v_rcp_f32_e32 v130, v130
	v_rcp_f32_e32 v131, v131
	v_rcp_f32_e32 v134, v134
	v_rcp_f32_e32 v135, v135
	v_rcp_f32_e32 v136, v136
	v_rcp_f32_e32 v137, v137
	v_rcp_f32_e32 v138, v138
	v_rcp_f32_e32 v139, v139
	v_add_u32_e32 v132, 0x80, v168
	v_mad_i64_i32 v[132:133], s[60:61], v132, s66, v[128:129]
	v_lshl_add_u64 v[132:133], v[132:133], 0, s[6:7]
	v_pk_mul_f32 v[130:131], v[60:61], v[130:131]
	v_pk_mul_f32 v[134:135], v[62:63], v[134:135]
	v_pk_mul_f32 v[136:137], v[56:57], v[136:137]
	v_pk_mul_f32 v[138:139], v[58:59], v[138:139]
	v_lshl_add_u64 v[132:133], v[132:133], 0, s[42:43]
	v_pk_mul_f32 v[130:131], v[130:131], v[44:45]
	v_pk_mul_f32 v[134:135], v[134:135], v[46:47]
	v_pk_mul_f32 v[136:137], v[136:137], v[40:41]
	v_pk_mul_f32 v[138:139], v[138:139], v[42:43]
	v_lshl_add_u64 v[140:141], v[132:133], 0, v[144:145]
	v_cvt_pk_bf16_f32 v130, v130, v131
	v_cvt_pk_bf16_f32 v131, v134, v135
	v_cvt_pk_bf16_f32 v132, v136, v137
	v_cvt_pk_bf16_f32 v133, v138, v139
	global_store_dwordx4 v[140:141], v[130:133], off
	v_mul_f32_e32 v134, 0xbfb8aa3b, v54
	v_mul_f32_e32 v135, 0xbfb8aa3b, v55
	v_mul_f32_e32 v130, 0xbfb8aa3b, v52
	v_mul_f32_e32 v131, 0xbfb8aa3b, v53
	v_mul_f32_e32 v136, 0xbfb8aa3b, v48
	v_mul_f32_e32 v137, 0xbfb8aa3b, v49
	v_mul_f32_e32 v138, 0xbfb8aa3b, v50
	v_mul_f32_e32 v139, 0xbfb8aa3b, v51
	v_exp_f32_e32 v130, v130
	v_exp_f32_e32 v131, v131
	v_exp_f32_e32 v134, v134
	v_exp_f32_e32 v135, v135
	v_exp_f32_e32 v136, v136
	v_exp_f32_e32 v137, v137
	v_exp_f32_e32 v138, v138
	v_exp_f32_e32 v139, v139
	v_add_f32_e32 v130, 1.0, v130
	v_add_f32_e32 v131, 1.0, v131
	v_add_f32_e32 v134, 1.0, v134
	v_add_f32_e32 v135, 1.0, v135
	v_add_f32_e32 v136, 1.0, v136
	v_add_f32_e32 v137, 1.0, v137
	v_add_f32_e32 v138, 1.0, v138
	v_add_f32_e32 v139, 1.0, v139
	v_rcp_f32_e32 v130, v130
	v_rcp_f32_e32 v131, v131
	v_rcp_f32_e32 v134, v134
	v_rcp_f32_e32 v135, v135
	v_rcp_f32_e32 v136, v136
	v_rcp_f32_e32 v137, v137
	v_rcp_f32_e32 v138, v138
	v_rcp_f32_e32 v139, v139
	v_add_u32_e32 v132, 0x90, v168
	v_mad_i64_i32 v[132:133], s[60:61], v132, s66, v[128:129]
	v_lshl_add_u64 v[132:133], v[132:133], 0, s[6:7]
	v_pk_mul_f32 v[130:131], v[52:53], v[130:131]
	v_pk_mul_f32 v[134:135], v[54:55], v[134:135]
	v_pk_mul_f32 v[136:137], v[48:49], v[136:137]
	v_pk_mul_f32 v[138:139], v[50:51], v[138:139]
	v_lshl_add_u64 v[132:133], v[132:133], 0, s[42:43]
	v_pk_mul_f32 v[130:131], v[130:131], v[28:29]
	v_pk_mul_f32 v[134:135], v[134:135], v[30:31]
	v_pk_mul_f32 v[136:137], v[136:137], v[24:25]
	v_pk_mul_f32 v[138:139], v[138:139], v[26:27]
	v_lshl_add_u64 v[140:141], v[132:133], 0, v[144:145]
	v_cvt_pk_bf16_f32 v130, v130, v131
	v_cvt_pk_bf16_f32 v131, v134, v135
	v_cvt_pk_bf16_f32 v132, v136, v137
	v_cvt_pk_bf16_f32 v133, v138, v139
	global_store_dwordx4 v[140:141], v[130:133], off
	v_mul_f32_e32 v134, 0xbfb8aa3b, v38
	v_mul_f32_e32 v135, 0xbfb8aa3b, v39
	v_mul_f32_e32 v130, 0xbfb8aa3b, v36
	v_mul_f32_e32 v131, 0xbfb8aa3b, v37
	v_mul_f32_e32 v136, 0xbfb8aa3b, v32
	v_mul_f32_e32 v137, 0xbfb8aa3b, v33
	v_mul_f32_e32 v138, 0xbfb8aa3b, v34
	v_mul_f32_e32 v139, 0xbfb8aa3b, v35
	v_exp_f32_e32 v130, v130
	v_exp_f32_e32 v131, v131
	v_exp_f32_e32 v134, v134
	v_exp_f32_e32 v135, v135
	v_exp_f32_e32 v136, v136
	v_exp_f32_e32 v137, v137
	v_exp_f32_e32 v138, v138
	v_exp_f32_e32 v139, v139
	v_add_f32_e32 v130, 1.0, v130
	v_add_f32_e32 v131, 1.0, v131
	v_add_f32_e32 v134, 1.0, v134
	v_add_f32_e32 v135, 1.0, v135
	v_add_f32_e32 v136, 1.0, v136
	v_add_f32_e32 v137, 1.0, v137
	v_add_f32_e32 v138, 1.0, v138
	v_add_f32_e32 v139, 1.0, v139
	v_rcp_f32_e32 v130, v130
	v_rcp_f32_e32 v131, v131
	v_rcp_f32_e32 v134, v134
	v_rcp_f32_e32 v135, v135
	v_rcp_f32_e32 v136, v136
	v_rcp_f32_e32 v137, v137
	v_rcp_f32_e32 v138, v138
	v_rcp_f32_e32 v139, v139
	v_add_u32_e32 v132, 0xa0, v168
	v_mad_i64_i32 v[132:133], s[60:61], v132, s66, v[128:129]
	v_lshl_add_u64 v[132:133], v[132:133], 0, s[6:7]
	v_pk_mul_f32 v[130:131], v[36:37], v[130:131]
	v_pk_mul_f32 v[134:135], v[38:39], v[134:135]
	v_pk_mul_f32 v[136:137], v[32:33], v[136:137]
	v_pk_mul_f32 v[138:139], v[34:35], v[138:139]
	v_lshl_add_u64 v[132:133], v[132:133], 0, s[42:43]
	v_pk_mul_f32 v[130:131], v[130:131], v[12:13]
	v_pk_mul_f32 v[134:135], v[134:135], v[14:15]
	v_pk_mul_f32 v[136:137], v[136:137], v[8:9]
	v_pk_mul_f32 v[138:139], v[138:139], v[10:11]
	v_lshl_add_u64 v[140:141], v[132:133], 0, v[144:145]
	v_cvt_pk_bf16_f32 v130, v130, v131
	v_cvt_pk_bf16_f32 v131, v134, v135
	v_cvt_pk_bf16_f32 v132, v136, v137
	v_cvt_pk_bf16_f32 v133, v138, v139
	global_store_dwordx4 v[140:141], v[130:133], off
	v_mul_f32_e32 v134, 0xbfb8aa3b, v16
	v_mul_f32_e32 v135, 0xbfb8aa3b, v17
	v_add_u32_e32 v132, 0xb0, v168
	v_mul_f32_e32 v130, 0xbfb8aa3b, v20
	v_mul_f32_e32 v131, 0xbfb8aa3b, v21
	v_mad_i64_i32 v[128:129], s[60:61], v132, s66, v[128:129]
	v_mul_f32_e32 v132, 0xbfb8aa3b, v22
	v_mul_f32_e32 v133, 0xbfb8aa3b, v23
	v_mul_f32_e32 v136, 0xbfb8aa3b, v18
	v_mul_f32_e32 v137, 0xbfb8aa3b, v19
	v_exp_f32_e32 v130, v130
	v_exp_f32_e32 v131, v131
	v_exp_f32_e32 v132, v132
	v_exp_f32_e32 v133, v133
	v_exp_f32_e32 v134, v134
	v_exp_f32_e32 v135, v135
	v_exp_f32_e32 v136, v136
	v_exp_f32_e32 v137, v137
	v_add_f32_e32 v130, 1.0, v130
	v_add_f32_e32 v131, 1.0, v131
	v_add_f32_e32 v132, 1.0, v132
	v_add_f32_e32 v133, 1.0, v133
	v_add_f32_e32 v134, 1.0, v134
	v_add_f32_e32 v135, 1.0, v135
	v_add_f32_e32 v136, 1.0, v136
	v_add_f32_e32 v137, 1.0, v137
	v_rcp_f32_e32 v130, v130
	v_rcp_f32_e32 v131, v131
	v_rcp_f32_e32 v132, v132
	v_rcp_f32_e32 v133, v133
	v_rcp_f32_e32 v134, v134
	v_rcp_f32_e32 v135, v135
	v_rcp_f32_e32 v136, v136
	v_rcp_f32_e32 v137, v137
	v_lshl_add_u64 v[128:129], v[128:129], 0, s[6:7]
	v_pk_mul_f32 v[130:131], v[20:21], v[130:131]
	v_pk_mul_f32 v[132:133], v[22:23], v[132:133]
	v_pk_mul_f32 v[134:135], v[16:17], v[134:135]
	v_pk_mul_f32 v[136:137], v[18:19], v[136:137]
	v_lshl_add_u64 v[128:129], v[128:129], 0, s[42:43]
	v_pk_mul_f32 v[130:131], v[130:131], v[4:5]
	v_pk_mul_f32 v[132:133], v[132:133], v[6:7]
	v_pk_mul_f32 v[134:135], v[134:135], v[0:1]
	v_pk_mul_f32 v[136:137], v[136:137], v[2:3]
	v_lshl_add_u64 v[138:139], v[128:129], 0, v[144:145]
	v_cvt_pk_bf16_f32 v128, v130, v131
	v_cvt_pk_bf16_f32 v129, v132, v133
	v_cvt_pk_bf16_f32 v130, v134, v135
	v_cvt_pk_bf16_f32 v131, v136, v137
	global_store_dwordx4 v[138:139], v[128:131], off
